# accumulator zeroing by 8 zero-operand MFMAs instead of 128 v_mov per unit; MLA prologue batched loads; earlier changes
# speedup vs baseline: 1.0174x; 1.0172x over previous
; template <class Epi, class Sched, bool ALIGN_EPI = false, bool SP2 = false>
; __device__ __forceinline__ void gemm_phase(PG8_LAS unsigned char* lds, const Gemm g, const Sched& S, const Epi& E) {
;     ...
; #pragma unroll
;         for (int a = 0; a < 2; ++a)
; #pragma unroll
;             for (int b = 0; b < 2; ++b)
; #pragma unroll
;                 for (int m = 0; m < 4; ++m)
; #pragma unroll
;                     for (int n = 0; n < 2; ++n) acc[a][b][m][n] = (f32x4){0.f, 0.f, 0.f, 0.f};
.LBB0_497:
	v_mov_b32_e32 v142, 0
	v_mov_b32_e32 v143, 0
	v_mov_b32_e32 v144, 0
	v_mov_b32_e32 v145, 0
	s_andn2_b64 vcc, exec, s[48:49]
	s_nop 1
	v_mfma_f32_32x32x16_bf16 v[2:17], v[142:145], v[142:145], 0
	v_mfma_f32_32x32x16_bf16 v[18:33], v[142:145], v[142:145], 0
	v_mfma_f32_32x32x16_bf16 v[34:49], v[142:145], v[142:145], 0
	v_mfma_f32_32x32x16_bf16 v[50:65], v[142:145], v[142:145], 0
	v_mfma_f32_32x32x16_bf16 v[66:81], v[142:145], v[142:145], 0
	v_mfma_f32_32x32x16_bf16 v[82:97], v[142:145], v[142:145], 0
	v_mfma_f32_32x32x16_bf16 v[100:115], v[142:145], v[142:145], 0
	v_mfma_f32_32x32x16_bf16 v[116:131], v[142:145], v[142:145], 0
	s_cbranch_vccnz .LBB0_500
	s_add_u32 s2, s36, 0x80
	s_addc_u32 s3, s37, 0
	s_add_u32 s4, s34, 0x100
	s_addc_u32 s16, s35, 0
	s_mov_b32 s17, 0

; template <class Epi, class Sched, bool ALIGN_EPI = false, bool SP2 = false>
; __device__ __forceinline__ void gemm_phase(PG8_LAS unsigned char* lds, const Gemm g, const Sched& S, const Epi& E) {
;     ...
; #pragma unroll
;         for (int a = 0; a < 2; ++a)
; #pragma unroll
;             for (int b = 0; b < 2; ++b)
; #pragma unroll
;                 for (int m = 0; m < 4; ++m)
; #pragma unroll
;                     for (int n = 0; n < 2; ++n) acc[a][b][m][n] = (f32x4){0.f, 0.f, 0.f, 0.f};
.LBB0_519:
	v_mov_b32_e32 v146, 0
	v_mov_b32_e32 v147, 0
	v_mov_b32_e32 v148, 0
	v_mov_b32_e32 v149, 0
	s_andn2_b64 vcc, exec, s[46:47]
	s_nop 1
	v_mfma_f32_32x32x16_bf16 v[2:17], v[146:149], v[146:149], 0
	v_mfma_f32_32x32x16_bf16 v[18:33], v[146:149], v[146:149], 0
	v_mfma_f32_32x32x16_bf16 v[34:49], v[146:149], v[146:149], 0
	v_mfma_f32_32x32x16_bf16 v[50:65], v[146:149], v[146:149], 0
	v_mfma_f32_32x32x16_bf16 v[66:81], v[146:149], v[146:149], 0
	v_mfma_f32_32x32x16_bf16 v[82:97], v[146:149], v[146:149], 0
	v_mfma_f32_32x32x16_bf16 v[100:115], v[146:149], v[146:149], 0
	v_mfma_f32_32x32x16_bf16 v[116:131], v[146:149], v[146:149], 0
	s_cbranch_vccnz .LBB0_522
	s_add_u32 s34, s34, 0x80
	s_addc_u32 s35, s35, 0
	s_add_u32 s4, s36, 0x100
	s_addc_u32 s16, s37, 0
	s_mov_b32 s17, 0

; template <class Epi, class Sched, bool ALIGN_EPI = false, bool SP2 = false>
; __device__ __forceinline__ void gemm_phase(PG8_LAS unsigned char* lds, const Gemm g, const Sched& S, const Epi& E) {
;     ...
; #pragma unroll
;         for (int a = 0; a < 2; ++a)
; #pragma unroll
;             for (int b = 0; b < 2; ++b)
; #pragma unroll
;                 for (int m = 0; m < 4; ++m)
; #pragma unroll
;                     for (int n = 0; n < 2; ++n) acc[a][b][m][n] = (f32x4){0.f, 0.f, 0.f, 0.f};
.LBB0_874:
	v_mov_b32_e32 v142, 0
	v_mov_b32_e32 v143, 0
	v_mov_b32_e32 v144, 0
	v_mov_b32_e32 v145, 0
	s_andn2_b64 vcc, exec, s[50:51]
	s_nop 1
	v_mfma_f32_32x32x16_bf16 v[2:17], v[142:145], v[142:145], 0
	v_mfma_f32_32x32x16_bf16 v[18:33], v[142:145], v[142:145], 0
	v_mfma_f32_32x32x16_bf16 v[34:49], v[142:145], v[142:145], 0
	v_mfma_f32_32x32x16_bf16 v[50:65], v[142:145], v[142:145], 0
	v_mfma_f32_32x32x16_bf16 v[66:81], v[142:145], v[142:145], 0
	v_mfma_f32_32x32x16_bf16 v[82:97], v[142:145], v[142:145], 0
	v_mfma_f32_32x32x16_bf16 v[100:115], v[142:145], v[142:145], 0
	v_mfma_f32_32x32x16_bf16 v[116:131], v[142:145], v[142:145], 0
	s_cbranch_vccnz .LBB0_877
	s_add_u32 s34, s34, 0x80
	s_addc_u32 s35, s35, 0
	s_add_u32 s4, s36, 0x100
	s_addc_u32 s16, s37, 0
	s_mov_b32 s17, 0

; template <class Epi, class Sched, bool ALIGN_EPI = false, bool SP2 = false>
; __device__ __forceinline__ void gemm_phase(PG8_LAS unsigned char* lds, const Gemm g, const Sched& S, const Epi& E) {
;     ...
; #pragma unroll
;         for (int a = 0; a < 2; ++a)
; #pragma unroll
;             for (int b = 0; b < 2; ++b)
; #pragma unroll
;                 for (int m = 0; m < 4; ++m)
; #pragma unroll
;                     for (int n = 0; n < 2; ++n) acc[a][b][m][n] = (f32x4){0.f, 0.f, 0.f, 0.f};
.LBB0_965:
	v_mov_b32_e32 v132, 0
	v_mov_b32_e32 v133, 0
	v_mov_b32_e32 v134, 0
	v_mov_b32_e32 v135, 0
	s_andn2_b64 vcc, exec, s[52:53]
	s_nop 1
	v_mfma_f32_32x32x16_bf16 v[2:17], v[132:135], v[132:135], 0
	v_mfma_f32_32x32x16_bf16 v[18:33], v[132:135], v[132:135], 0
	v_mfma_f32_32x32x16_bf16 v[34:49], v[132:135], v[132:135], 0
	v_mfma_f32_32x32x16_bf16 v[50:65], v[132:135], v[132:135], 0
	v_mfma_f32_32x32x16_bf16 v[66:81], v[132:135], v[132:135], 0
	v_mfma_f32_32x32x16_bf16 v[82:97], v[132:135], v[132:135], 0
	v_mfma_f32_32x32x16_bf16 v[100:115], v[132:135], v[132:135], 0
	v_mfma_f32_32x32x16_bf16 v[116:131], v[132:135], v[132:135], 0
	s_cbranch_vccnz .LBB0_968
	s_add_u32 s34, s34, 0x80
	s_addc_u32 s35, s35, 0
	s_add_u32 s4, s36, 0x100
	s_addc_u32 s16, s37, 0
	s_mov_b32 s17, 0

; template <class Epi, class Sched, bool ALIGN_EPI = false, bool SP2 = false>
; __device__ __forceinline__ void gemm_phase(PG8_LAS unsigned char* lds, const Gemm g, const Sched& S, const Epi& E) {
;     ...
; #pragma unroll
;         for (int a = 0; a < 2; ++a)
; #pragma unroll
;             for (int b = 0; b < 2; ++b)
; #pragma unroll
;                 for (int m = 0; m < 4; ++m)
; #pragma unroll
;                     for (int n = 0; n < 2; ++n) acc[a][b][m][n] = (f32x4){0.f, 0.f, 0.f, 0.f};
.LBB0_1050:
	v_mov_b32_e32 v132, 0
	v_mov_b32_e32 v133, 0
	v_mov_b32_e32 v134, 0
	v_mov_b32_e32 v135, 0
	s_andn2_b64 vcc, exec, s[50:51]
	s_nop 1
	v_mfma_f32_32x32x16_bf16 v[2:17], v[132:135], v[132:135], 0
	v_mfma_f32_32x32x16_bf16 v[18:33], v[132:135], v[132:135], 0
	v_mfma_f32_32x32x16_bf16 v[34:49], v[132:135], v[132:135], 0
	v_mfma_f32_32x32x16_bf16 v[50:65], v[132:135], v[132:135], 0
	v_mfma_f32_32x32x16_bf16 v[66:81], v[132:135], v[132:135], 0
	v_mfma_f32_32x32x16_bf16 v[82:97], v[132:135], v[132:135], 0
	v_mfma_f32_32x32x16_bf16 v[100:115], v[132:135], v[132:135], 0
	v_mfma_f32_32x32x16_bf16 v[116:131], v[132:135], v[132:135], 0
	s_cbranch_vccnz .LBB0_1053
	s_add_u32 s2, s36, 0x80
	s_addc_u32 s3, s37, 0
	s_add_u32 s4, s34, 0x100
	s_addc_u32 s16, s35, 0
	s_mov_b32 s17, 0

; template <class Epi, class Sched, bool ALIGN_EPI = false, bool SP2 = false>
; __device__ __forceinline__ void gemm_phase(PG8_LAS unsigned char* lds, const Gemm g, const Sched& S, const Epi& E) {
;     ...
; #pragma unroll
;         for (int a = 0; a < 2; ++a)
; #pragma unroll
;             for (int b = 0; b < 2; ++b)
; #pragma unroll
;                 for (int m = 0; m < 4; ++m)
; #pragma unroll
;                     for (int n = 0; n < 2; ++n) acc[a][b][m][n] = (f32x4){0.f, 0.f, 0.f, 0.f};
.LBB0_1125:
	v_mov_b32_e32 v144, 0
	v_mov_b32_e32 v145, 0
	v_mov_b32_e32 v146, 0
	v_mov_b32_e32 v147, 0
	s_andn2_b64 vcc, exec, s[52:53]
	s_nop 1
	v_mfma_f32_32x32x16_bf16 v[2:17], v[144:147], v[144:147], 0
	v_mfma_f32_32x32x16_bf16 v[18:33], v[144:147], v[144:147], 0
	v_mfma_f32_32x32x16_bf16 v[34:49], v[144:147], v[144:147], 0
	v_mfma_f32_32x32x16_bf16 v[50:65], v[144:147], v[144:147], 0
	v_mfma_f32_32x32x16_bf16 v[66:81], v[144:147], v[144:147], 0
	v_mfma_f32_32x32x16_bf16 v[82:97], v[144:147], v[144:147], 0
	v_mfma_f32_32x32x16_bf16 v[100:115], v[144:147], v[144:147], 0
	v_mfma_f32_32x32x16_bf16 v[116:131], v[144:147], v[144:147], 0
	s_cbranch_vccnz .LBB0_1128
	s_add_u32 s2, s36, 0x80
	s_addc_u32 s3, s37, 0
	s_add_u32 s4, s34, 0x100
	s_addc_u32 s16, s35, 0
	s_mov_b32 s17, 0

; template <class Epi, class Sched, bool ALIGN_EPI = false, bool SP2 = false>
; __device__ __forceinline__ void gemm_phase(PG8_LAS unsigned char* lds, const Gemm g, const Sched& S, const Epi& E) {
;     ...
; #pragma unroll
;         for (int a = 0; a < 2; ++a)
; #pragma unroll
;             for (int b = 0; b < 2; ++b)
; #pragma unroll
;                 for (int m = 0; m < 4; ++m)
; #pragma unroll
;                     for (int n = 0; n < 2; ++n) acc[a][b][m][n] = (f32x4){0.f, 0.f, 0.f, 0.f};
.LBB0_1178:
	v_mov_b32_e32 v144, 0
	v_mov_b32_e32 v145, 0
	v_mov_b32_e32 v146, 0
	v_mov_b32_e32 v147, 0
	s_andn2_b64 vcc, exec, s[46:47]
	s_nop 1
	v_mfma_f32_32x32x16_bf16 v[2:17], v[144:147], v[144:147], 0
	v_mfma_f32_32x32x16_bf16 v[18:33], v[144:147], v[144:147], 0
	v_mfma_f32_32x32x16_bf16 v[34:49], v[144:147], v[144:147], 0
	v_mfma_f32_32x32x16_bf16 v[50:65], v[144:147], v[144:147], 0
	v_mfma_f32_32x32x16_bf16 v[66:81], v[144:147], v[144:147], 0
	v_mfma_f32_32x32x16_bf16 v[82:97], v[144:147], v[144:147], 0
	v_mfma_f32_32x32x16_bf16 v[100:115], v[144:147], v[144:147], 0
	v_mfma_f32_32x32x16_bf16 v[116:131], v[144:147], v[144:147], 0
	s_cbranch_vccnz .LBB0_1181
	s_add_u32 s34, s34, 0x80
	s_addc_u32 s35, s35, 0
	s_add_u32 s4, s36, 0x100
	s_addc_u32 s16, s37, 0
	s_mov_b32 s17, 0

; template <class Epi, class Sched, bool ALIGN_EPI = false, bool SP2 = false>
; __device__ __forceinline__ void gemm_phase(PG8_LAS unsigned char* lds, const Gemm g, const Sched& S, const Epi& E) {
;     ...
; #pragma unroll
;         for (int a = 0; a < 2; ++a)
; #pragma unroll
;             for (int b = 0; b < 2; ++b)
; #pragma unroll
;                 for (int m = 0; m < 4; ++m)
; #pragma unroll
;                     for (int n = 0; n < 2; ++n) acc[a][b][m][n] = (f32x4){0.f, 0.f, 0.f, 0.f};
.LBB0_1207:
	v_mov_b32_e32 v132, 0
	v_mov_b32_e32 v133, 0
	v_mov_b32_e32 v134, 0
	v_mov_b32_e32 v135, 0
	s_andn2_b64 vcc, exec, s[46:47]
	s_nop 1
	v_mfma_f32_32x32x16_bf16 v[2:17], v[132:135], v[132:135], 0
	v_mfma_f32_32x32x16_bf16 v[18:33], v[132:135], v[132:135], 0
	v_mfma_f32_32x32x16_bf16 v[34:49], v[132:135], v[132:135], 0
	v_mfma_f32_32x32x16_bf16 v[50:65], v[132:135], v[132:135], 0
	v_mfma_f32_32x32x16_bf16 v[66:81], v[132:135], v[132:135], 0
	v_mfma_f32_32x32x16_bf16 v[82:97], v[132:135], v[132:135], 0
	v_mfma_f32_32x32x16_bf16 v[100:115], v[132:135], v[132:135], 0
	v_mfma_f32_32x32x16_bf16 v[116:131], v[132:135], v[132:135], 0
	s_cbranch_vccnz .LBB0_1210
	s_add_u32 s2, s36, 0x80
	s_addc_u32 s3, s37, 0
	s_add_u32 s4, s34, 0x100
	s_addc_u32 s16, s35, 0
	s_mov_b32 s17, 0

; template <class Epi, class Sched, bool ALIGN_EPI = false, bool SP2 = false>
; __device__ __forceinline__ void gemm_phase(PG8_LAS unsigned char* lds, const Gemm g, const Sched& S, const Epi& E) {
;     ...
; #pragma unroll
;         for (int a = 0; a < 2; ++a)
; #pragma unroll
;             for (int b = 0; b < 2; ++b)
; #pragma unroll
;                 for (int m = 0; m < 4; ++m)
; #pragma unroll
;                     for (int n = 0; n < 2; ++n) acc[a][b][m][n] = (f32x4){0.f, 0.f, 0.f, 0.f};
.LBB0_1481:
	v_mov_b32_e32 v142, 0
	v_mov_b32_e32 v143, 0
	v_mov_b32_e32 v144, 0
	v_mov_b32_e32 v145, 0
	s_andn2_b64 vcc, exec, s[46:47]
	s_nop 1
	v_mfma_f32_32x32x16_bf16 v[2:17], v[142:145], v[142:145], 0
	v_mfma_f32_32x32x16_bf16 v[18:33], v[142:145], v[142:145], 0
	v_mfma_f32_32x32x16_bf16 v[34:49], v[142:145], v[142:145], 0
	v_mfma_f32_32x32x16_bf16 v[50:65], v[142:145], v[142:145], 0
	v_mfma_f32_32x32x16_bf16 v[66:81], v[142:145], v[142:145], 0
	v_mfma_f32_32x32x16_bf16 v[82:97], v[142:145], v[142:145], 0
	v_mfma_f32_32x32x16_bf16 v[100:115], v[142:145], v[142:145], 0
	v_mfma_f32_32x32x16_bf16 v[116:131], v[142:145], v[142:145], 0
	s_cbranch_vccnz .LBB0_1484
	s_add_u32 s2, s36, 0x80
	s_addc_u32 s3, s37, 0
	s_add_u32 s4, s34, 0x100
	s_addc_u32 s16, s35, 0
	s_mov_b32 s17, 0

; template <class Epi, class Sched, bool ALIGN_EPI = false, bool SP2 = false>
; __device__ __forceinline__ void gemm_phase(PG8_LAS unsigned char* lds, const Gemm g, const Sched& S, const Epi& E) {
;     ...
; #pragma unroll
;         for (int a = 0; a < 2; ++a)
; #pragma unroll
;             for (int b = 0; b < 2; ++b)
; #pragma unroll
;                 for (int m = 0; m < 4; ++m)
; #pragma unroll
;                     for (int n = 0; n < 2; ++n) acc[a][b][m][n] = (f32x4){0.f, 0.f, 0.f, 0.f};
.LBB0_1760:
	v_mov_b32_e32 v142, 0
	v_mov_b32_e32 v143, 0
	v_mov_b32_e32 v144, 0
	v_mov_b32_e32 v145, 0
	s_andn2_b64 vcc, exec, s[48:49]
	s_nop 1
	v_mfma_f32_32x32x16_bf16 v[2:17], v[142:145], v[142:145], 0
	v_mfma_f32_32x32x16_bf16 v[18:33], v[142:145], v[142:145], 0
	v_mfma_f32_32x32x16_bf16 v[34:49], v[142:145], v[142:145], 0
	v_mfma_f32_32x32x16_bf16 v[50:65], v[142:145], v[142:145], 0
	v_mfma_f32_32x32x16_bf16 v[66:81], v[142:145], v[142:145], 0
	v_mfma_f32_32x32x16_bf16 v[82:97], v[142:145], v[142:145], 0
	v_mfma_f32_32x32x16_bf16 v[100:115], v[142:145], v[142:145], 0
	v_mfma_f32_32x32x16_bf16 v[116:131], v[142:145], v[142:145], 0
	s_cbranch_vccnz .LBB0_1763
	s_add_u32 s34, s34, 0x80
	s_addc_u32 s35, s35, 0
	s_add_u32 s4, s36, 0x100
	s_addc_u32 s16, s37, 0
	s_mov_b32 s17, 0

; template <class Epi, class Sched, bool ALIGN_EPI = false, bool SP2 = false>
; __device__ __forceinline__ void gemm_phase(PG8_LAS unsigned char* lds, const Gemm g, const Sched& S, const Epi& E) {
;     ...
; #pragma unroll
;         for (int a = 0; a < 2; ++a)
; #pragma unroll
;             for (int b = 0; b < 2; ++b)
; #pragma unroll
;                 for (int m = 0; m < 4; ++m)
; #pragma unroll
;                     for (int n = 0; n < 2; ++n) acc[a][b][m][n] = (f32x4){0.f, 0.f, 0.f, 0.f};
.LBB0_1851:
	v_mov_b32_e32 v142, 0
	v_mov_b32_e32 v143, 0
	v_mov_b32_e32 v144, 0
	v_mov_b32_e32 v145, 0
	s_andn2_b64 vcc, exec, s[54:55]
	s_nop 1
	v_mfma_f32_32x32x16_bf16 v[2:17], v[142:145], v[142:145], 0
	v_mfma_f32_32x32x16_bf16 v[18:33], v[142:145], v[142:145], 0
	v_mfma_f32_32x32x16_bf16 v[34:49], v[142:145], v[142:145], 0
	v_mfma_f32_32x32x16_bf16 v[50:65], v[142:145], v[142:145], 0
	v_mfma_f32_32x32x16_bf16 v[66:81], v[142:145], v[142:145], 0
	v_mfma_f32_32x32x16_bf16 v[82:97], v[142:145], v[142:145], 0
	v_mfma_f32_32x32x16_bf16 v[100:115], v[142:145], v[142:145], 0
	v_mfma_f32_32x32x16_bf16 v[116:131], v[142:145], v[142:145], 0
	s_cbranch_vccnz .LBB0_1854
	s_add_u32 s34, s34, 0x80
	s_addc_u32 s35, s35, 0
	s_add_u32 s4, s36, 0x100
	s_addc_u32 s16, s37, 0
	s_mov_b32 s17, 0
